# sample attention K/V loads: nt -> sc1 nt (stream past L2)
# baseline (speedup 1.0000x reference)
; __device__ __forceinline__ void sa_rows(int kk, int b, const float* ck, const float* cv, const float* out, const float*& kr, const float*& vr, int& e) {
;     e = kk < 516 ? kk : 528 + 16 * ((kk - 516) >> 2) + ((kk - 516) & 3);
;     const int idx = 2051 - e;
;     if (idx >= WB) { kr = out + O_KS + (size_t)(b * 4 + idx - WB) * 512; vr = out + O_VS + (size_t)(b * 4 + idx - WB) * 512; }
;     else { kr = ck + ((size_t)b * WB + idx) * 512; vr = cv + ((size_t)b * WB + idx) * 512; }
; }
; __device__ __forceinline__ void attn_sample_phase(const bf16* QKVb, const float* ck, const float* cv, const float* out, bf16* SPART, float2* SML, int gw, int NGW, int lane) {
;     ...
;         for (int g = 0; g < SA_KPC / 4; ++g) {
;             f32x4 kx[4][2], vx[4][2]; int ee[4];
; #pragma unroll
;             for (int t = 0; t < 4; ++t) {
;                 const float *kr, *vr; sa_rows(c * SA_KPC + g * 4 + t, b, ck, cv, out, kr, vr, ee[t]);
;                 kx[t][0] = __builtin_nontemporal_load((const f32x4*)(kr + 4 * lane)); kx[t][1] = __builtin_nontemporal_load((const f32x4*)(kr + 256 + 4 * lane));
;                 vx[t][0] = __builtin_nontemporal_load((const f32x4*)(vr + 4 * lane)); vx[t][1] = __builtin_nontemporal_load((const f32x4*)(vr + 256 + 4 * lane));
;             }
.LBB0_1082:
	v_lshlrev_b32_e32 v3, 2, v102
	global_load_dwordx4 v[96:99], v3, s[8:9] sc1 nt
	global_load_dwordx4 v[88:91], v3, s[8:9] offset:1024 sc1 nt
	global_load_dwordx4 v[92:95], v3, s[10:11] sc1 nt
	global_load_dwordx4 v[84:87], v3, s[10:11] offset:1024 sc1 nt
	s_add_i32 s2, s26, 1
	s_add_i32 s3, s28, 0x211
	s_cmpk_lt_i32 s2, 0x204
	s_cselect_b32 s3, s2, s3
	s_cmp_lt_i32 s3, 4
	s_mov_b64 s[12:13], -1
	s_cbranch_scc1 .LBB0_1084
	s_sub_i32 s8, 0x803, s3
	s_ashr_i32 s9, s8, 31
	s_lshl_b64 s[8:9], s[8:9], 9
	s_add_u32 s8, s8, s6
	s_addc_u32 s9, s9, s7
	s_lshl_b64 s[10:11], s[8:9], 2
	s_add_u32 s8, s76, s10
	s_addc_u32 s9, s77, s11
	s_add_u32 s10, s78, s10
	s_addc_u32 s11, s79, s11
	s_mov_b64 s[12:13], 0

; __device__ __forceinline__ void sa_rows(int kk, int b, const float* ck, const float* cv, const float* out, const float*& kr, const float*& vr, int& e) {
;     e = kk < 516 ? kk : 528 + 16 * ((kk - 516) >> 2) + ((kk - 516) & 3);
;     const int idx = 2051 - e;
;     if (idx >= WB) { kr = out + O_KS + (size_t)(b * 4 + idx - WB) * 512; vr = out + O_VS + (size_t)(b * 4 + idx - WB) * 512; }
;     else { kr = ck + ((size_t)b * WB + idx) * 512; vr = cv + ((size_t)b * WB + idx) * 512; }
; }
; __device__ __forceinline__ void attn_sample_phase(const bf16* QKVb, const float* ck, const float* cv, const float* out, bf16* SPART, float2* SML, int gw, int NGW, int lane) {
;     ...
;         for (int g = 0; g < SA_KPC / 4; ++g) {
;             f32x4 kx[4][2], vx[4][2]; int ee[4];
; #pragma unroll
;             for (int t = 0; t < 4; ++t) {
;                 const float *kr, *vr; sa_rows(c * SA_KPC + g * 4 + t, b, ck, cv, out, kr, vr, ee[t]);
;                 kx[t][0] = __builtin_nontemporal_load((const f32x4*)(kr + 4 * lane)); kx[t][1] = __builtin_nontemporal_load((const f32x4*)(kr + 256 + 4 * lane));
;                 vx[t][0] = __builtin_nontemporal_load((const f32x4*)(vr + 4 * lane)); vx[t][1] = __builtin_nontemporal_load((const f32x4*)(vr + 256 + 4 * lane));
;             }
.LBB0_1086:
	global_load_dwordx4 v[80:83], v3, s[8:9] sc1 nt
	global_load_dwordx4 v[72:75], v3, s[8:9] offset:1024 sc1 nt
	global_load_dwordx4 v[76:79], v3, s[10:11] sc1 nt
	global_load_dwordx4 v[68:71], v3, s[10:11] offset:1024 sc1 nt
	s_add_i32 s2, s26, 2
	s_add_i32 s8, s28, 0x212
	s_cmpk_lt_i32 s2, 0x204
	s_cselect_b32 s2, s2, s8
	s_cmp_lt_i32 s2, 4
	s_mov_b64 s[12:13], -1
	s_cbranch_scc1 .LBB0_1088
	s_sub_i32 s8, 0x803, s2
	s_ashr_i32 s9, s8, 31
	s_lshl_b64 s[8:9], s[8:9], 9
	s_add_u32 s8, s8, s6
	s_addc_u32 s9, s9, s7
	s_lshl_b64 s[10:11], s[8:9], 2
	s_add_u32 s8, s76, s10
	s_addc_u32 s9, s77, s11
	s_add_u32 s10, s78, s10
	s_addc_u32 s11, s79, s11
	s_mov_b64 s[12:13], 0

; __device__ __forceinline__ void sa_rows(int kk, int b, const float* ck, const float* cv, const float* out, const float*& kr, const float*& vr, int& e) {
;     e = kk < 516 ? kk : 528 + 16 * ((kk - 516) >> 2) + ((kk - 516) & 3);
;     const int idx = 2051 - e;
;     if (idx >= WB) { kr = out + O_KS + (size_t)(b * 4 + idx - WB) * 512; vr = out + O_VS + (size_t)(b * 4 + idx - WB) * 512; }
;     else { kr = ck + ((size_t)b * WB + idx) * 512; vr = cv + ((size_t)b * WB + idx) * 512; }
; }
; __device__ __forceinline__ void attn_sample_phase(const bf16* QKVb, const float* ck, const float* cv, const float* out, bf16* SPART, float2* SML, int gw, int NGW, int lane) {
;     ...
;         for (int g = 0; g < SA_KPC / 4; ++g) {
;             f32x4 kx[4][2], vx[4][2]; int ee[4];
; #pragma unroll
;             for (int t = 0; t < 4; ++t) {
;                 const float *kr, *vr; sa_rows(c * SA_KPC + g * 4 + t, b, ck, cv, out, kr, vr, ee[t]);
;                 kx[t][0] = __builtin_nontemporal_load((const f32x4*)(kr + 4 * lane)); kx[t][1] = __builtin_nontemporal_load((const f32x4*)(kr + 256 + 4 * lane));
;                 vx[t][0] = __builtin_nontemporal_load((const f32x4*)(vr + 4 * lane)); vx[t][1] = __builtin_nontemporal_load((const f32x4*)(vr + 256 + 4 * lane));
;             }
.LBB0_1090:
	global_load_dwordx4 v[64:67], v3, s[8:9] sc1 nt
	global_load_dwordx4 v[56:59], v3, s[8:9] offset:1024 sc1 nt
	global_load_dwordx4 v[60:63], v3, s[10:11] sc1 nt
	global_load_dwordx4 v[52:55], v3, s[10:11] offset:1024 sc1 nt
	s_add_i32 s26, s26, 3
	s_addk_i32 s28, 0x213
	s_cmpk_lt_i32 s26, 0x204
	s_cselect_b32 s26, s26, s28
	s_cmp_lt_i32 s26, 4
	s_mov_b64 s[12:13], -1
	s_cbranch_scc1 .LBB0_1092
	s_sub_i32 s8, 0x803, s26
	s_ashr_i32 s9, s8, 31
	s_lshl_b64 s[8:9], s[8:9], 9
	s_add_u32 s8, s8, s6
	s_addc_u32 s9, s9, s7
	s_lshl_b64 s[10:11], s[8:9], 2
	s_add_u32 s8, s76, s10
	s_addc_u32 s9, s77, s11
	s_add_u32 s10, s78, s10
	s_addc_u32 s11, s79, s11
	s_mov_b64 s[12:13], 0

; __device__ __forceinline__ float row16_sum(float v) { v += dppf<0xB1>(v); v += dppf<0x4E>(v); v += dppf<0x141>(v); v += dppf<0x128>(v); return v; }
; __device__ __forceinline__ void attn_sample_phase(const bf16* QKVb, const float* ck, const float* cv, const float* out, bf16* SPART, float2* SML, int gw, int NGW, int lane) {
;     ...
;                 kx[t][0] = __builtin_nontemporal_load((const f32x4*)(kr + 4 * lane)); kx[t][1] = __builtin_nontemporal_load((const f32x4*)(kr + 256 + 4 * lane));
;                 vx[t][0] = __builtin_nontemporal_load((const f32x4*)(vr + 4 * lane)); vx[t][1] = __builtin_nontemporal_load((const f32x4*)(vr + 256 + 4 * lane));
;             }
; #pragma unroll
;             for (int t = 0; t < 4; ++t)
; #pragma unroll
;                 for (int i = 0; i < 4; ++i) {
;                     const int dl = ee[t] - 3 + i;
;                     const int mult = dl >= 0 ? (int)(dl <= 128) + (int)(((dl & 3) == 0) && dl <= 512) + (int)(((dl & 15) == 0) && dl <= 2048) : 0;
;                     if (mult) {
;                         const float fm = (float)mult;
; #pragma unroll
;                         for (int u = 0; u < 2; ++u) {
;                             const f32x4 pr = q[i][u] * kx[t][u];
;                             const float s = row16_sum((pr[0] + pr[1]) + (pr[2] + pr[3]));
;                             const float mn = fmaxf(m[i][u], s), scl = __builtin_amdgcn_exp2f(m[i][u] - mn), p = fm * __builtin_amdgcn_exp2f(s - mn);
;                             m[i][u] = mn; l[i][u] = l[i][u] * scl + p; o[i][u] = o[i][u] * scl + vx[t][u] * p;
;                         }
.LBB0_1094:
	global_load_dwordx4 v[48:51], v3, s[8:9] sc1 nt
	global_load_dwordx4 v[40:43], v3, s[8:9] offset:1024 sc1 nt
	global_load_dwordx4 v[44:47], v3, s[10:11] sc1 nt
	global_load_dwordx4 v[36:39], v3, s[10:11] offset:1024 sc1 nt
	s_add_i32 s8, s27, 0xffffff7c
	s_cmp_lt_u32 s8, 0xffffff7f
	s_cbranch_scc1 .LBB0_1100
	s_waitcnt vmcnt(15)
	v_pk_mul_f32 v[174:175], v[98:99], v[110:111]
	v_pk_mul_f32 v[176:177], v[96:97], v[108:109]
	v_max_f32_e32 v103, v173, v173
	v_pk_mov_b32 v[178:179], v[176:177], v[174:175] op_sel:[1,0]
	v_mov_b32_e32 v177, v175
	v_pk_add_f32 v[174:175], v[178:179], v[176:177]
	s_waitcnt vmcnt(14)
	v_pk_mul_f32 v[180:181], v[90:91], v[114:115]
	v_add_f32_e32 v3, v174, v175
	v_pk_mul_f32 v[182:183], v[88:89], v[112:113]
	s_nop 0
	v_add_f32_dpp v3, v3, v3 quad_perm:[1,0,3,2] row_mask:0xf bank_mask:0xf bound_ctrl:1
	v_pk_mov_b32 v[184:185], v[182:183], v[180:181] op_sel:[1,0]
	v_mov_b32_e32 v183, v181
	v_add_f32_dpp v3, v3, v3 quad_perm:[2,3,0,1] row_mask:0xf bank_mask:0xf bound_ctrl:1
	v_pk_add_f32 v[180:181], v[184:185], v[182:183]
	s_nop 0
	v_add_f32_dpp v3, v3, v3 row_half_mirror row_mask:0xf bank_mask:0xf bound_ctrl:1
	s_nop 1
	v_add_f32_dpp v3, v3, v3 row_ror:8 row_mask:0xf bank_mask:0xf bound_ctrl:1
	v_max_f32_e32 v175, v103, v3
	v_sub_f32_e32 v3, v3, v175
	v_exp_f32_e32 v176, v3
	v_add_f32_e32 v3, v180, v181
	v_sub_f32_e32 v103, v173, v175
	v_exp_f32_e32 v178, v103
	v_add_f32_dpp v3, v3, v3 quad_perm:[1,0,3,2] row_mask:0xf bank_mask:0xf bound_ctrl:1
	v_max_f32_e32 v103, v159, v159
	v_mov_b32_e32 v174, v176
	v_add_f32_dpp v3, v3, v3 quad_perm:[2,3,0,1] row_mask:0xf bank_mask:0xf bound_ctrl:1
	v_fmac_f32_e32 v174, v172, v178
	s_waitcnt vmcnt(13)
	v_pk_mul_f32 v[172:173], v[92:93], v[176:177] op_sel_hi:[1,0]
	v_add_f32_dpp v3, v3, v3 row_half_mirror row_mask:0xf bank_mask:0xf bound_ctrl:1
	v_pk_mul_f32 v[176:177], v[94:95], v[176:177] op_sel_hi:[1,0]
	s_nop 0
	v_add_f32_dpp v3, v3, v3 row_ror:8 row_mask:0xf bank_mask:0xf bound_ctrl:1
	v_max_f32_e32 v179, v103, v3
	v_sub_f32_e32 v3, v3, v179
	v_sub_f32_e32 v103, v159, v179
	v_exp_f32_e32 v180, v3
	v_exp_f32_e32 v182, v103
	v_pk_fma_f32 v[34:35], v[34:35], v[178:179], v[176:177] op_sel_hi:[1,0,1]
	v_pk_fma_f32 v[32:33], v[32:33], v[178:179], v[172:173] op_sel_hi:[1,0,1]
	v_mov_b32_e32 v178, v180
	v_fmac_f32_e32 v178, v158, v182
	s_waitcnt vmcnt(12)
	v_pk_mul_f32 v[158:159], v[84:85], v[180:181] op_sel_hi:[1,0]
	v_pk_mul_f32 v[172:173], v[86:87], v[180:181] op_sel_hi:[1,0]
	v_pk_fma_f32 v[28:29], v[28:29], v[182:183], v[158:159] op_sel_hi:[1,0,1]
	v_pk_fma_f32 v[30:31], v[30:31], v[182:183], v[172:173] op_sel_hi:[1,0,1]
	v_mov_b32_e32 v172, v174
	v_mov_b32_e32 v173, v175
	v_mov_b32_e32 v158, v178
	v_mov_b32_e32 v159, v179
	s_add_i32 s8, s27, 0xffffff7d
	s_cmp_lt_u32 s8, 0xffffff7f
	s_cbranch_scc0 .LBB0_1101
